# PREP transpose: tile->descriptor search resumes from the previous tile's descriptor instead of restarting at 0
# speedup vs baseline: 1.0045x; 1.0045x over previous
.LBB0_1313:
	v_readlane_b32 s2, v254, 11
	v_readlane_b32 s3, v254, 12
	s_andn2_b64 vcc, exec, s[2:3]
	v_readlane_b32 s2, v254, 40
	v_readlane_b32 s3, v254, 41
	s_cbranch_vccnz .LBB0_1367
	s_mov_b32 s100, 0
	s_mov_b32 s2, 0
	s_mov_b32 s14, 0
	s_branch .LBB0_1317

.LBB0_1319:
	s_andn2_saveexec_b64 s[2:3], s[2:3]
	s_cbranch_execz .LBB0_1316
	v_readlane_b32 s4, v254, 13
	v_readlane_b32 s5, v254, 14
	s_andn2_b64 vcc, exec, s[4:5]
	s_cbranch_vccnz .LBB0_1326
	v_readlane_b32 s8, v254, 53
	v_readlane_b32 s9, v254, 54
	v_readfirstlane_b32 s15, v0
	s_and_b32 s10, s100, 0xff
	s_lshr_b32 s24, s100, 8
	s_lshl_b32 s11, s10, 5
	s_add_u32 s8, s8, s11
	s_addc_u32 s9, s9, 0
	s_sub_u32 s15, s15, s24
	v_readlane_b32 s38, v254, 42
.Lprep_walk:
	s_load_dword s28, s[8:9], 0x0
	s_load_dword s29, s[8:9], 0x8
	s_waitcnt lgkmcnt(0)
	s_ashr_i32 s28, s28, 6
	s_ashr_i32 s29, s29, 6
	s_mul_i32 s28, s29, s28
	s_cmp_lt_i32 s15, s28
	s_cbranch_scc1 .Lprep_walk_done
	s_sub_u32 s15, s15, s28
	s_add_u32 s24, s24, s28
	s_add_u32 s10, s10, 1
	s_add_u32 s8, s8, 32
	s_addc_u32 s9, s9, 0
	s_cmp_lt_u32 s10, s38
	s_cbranch_scc1 .Lprep_walk
.Lprep_walk_done:
	s_lshl_b32 s24, s24, 8
	s_or_b32 s100, s24, s10
	s_waitcnt vmcnt(3)
	v_mov_b32_e32 v0, s15
	v_mov_b32_e32 v2, s10
	v_mov_b32_e32 v3, 0
	s_branch .LBB0_1327
